# prologue streaming loads (x to bf16, weight transposes) marked non-temporal so they do not displace cached operands
# speedup vs baseline: 1.0133x; 1.0002x over previous
; DEV void transpose_item(const TJob& J, LAS float* scr, int item, int lane) {
;     const int nblk = J.ncols / 32, kb = item / nblk, nb = item % nblk, k0 = 64 * kb, n0 = 32 * nb;
;     const int sc0 = (n0 / J.grp) * J.gstride + (n0 % J.grp) + J.src_c0; const int n4 = 4 * (lane & 7); const bool ok = (n0 + n4) < J.nvalid;
;     f32x4 v[8];
; #pragma unroll
;     for (int i = 0; i < 8; ++i) { const int kk = 8 * i + (lane >> 3); v[i] = ok ? *(const f32x4*)(J.W + (size_t)(k0 + kk) * J.ldw + sc0 + n4) : (f32x4){0.f, 0.f, 0.f, 0.f}; }
.LBB0_18:
	s_mul_hi_u32 s9, s8, 48
	s_mul_i32 s8, s8, 48
	s_add_u32 s20, s0, s8
	s_addc_u32 s21, s1, s9
	s_load_dwordx4 s[8:11], s[20:21], 0x17c
	s_load_dword s23, s[20:21], 0x194
	s_load_dwordx2 s[28:29], s[20:21], 0x168
	s_load_dwordx2 s[30:31], s[20:21], 0x18c
	v_mov_b32_e32 v6, 0
	v_mov_b32_e32 v7, 0
	s_waitcnt lgkmcnt(0)
	s_ashr_i32 s22, s11, 31
	s_lshr_b32 s22, s22, 27
	s_add_i32 s11, s11, s22
	s_ashr_i32 s11, s11, 5
	s_abs_i32 s22, s11
	v_cvt_f32_u32_e32 v2, s22
	s_sub_i32 s33, 0, s22
	s_sub_i32 s23, s3, s23
	s_abs_i32 s26, s23
	v_rcp_iflag_f32_e32 v2, v2
	s_xor_b32 s27, s23, s11
	s_ashr_i32 s27, s27, 31
	v_mov_b32_e32 v8, 0
	v_mul_f32_e32 v2, 0x4f7ffffe, v2
	v_cvt_u32_f32_e32 v2, v2
	v_mov_b32_e32 v9, 0
	v_readfirstlane_b32 s34, v2
	s_mul_i32 s33, s33, s34
	s_mul_hi_u32 s33, s34, s33
	s_add_i32 s34, s34, s33
	s_mul_hi_u32 s33, s26, s34
	s_mul_i32 s34, s33, s22
	s_sub_i32 s26, s26, s34
	s_add_i32 s35, s33, 1
	s_sub_i32 s34, s26, s22
	s_cmp_ge_u32 s26, s22
	s_cselect_b32 s33, s35, s33
	s_cselect_b32 s26, s34, s26
	s_add_i32 s34, s33, 1
	s_cmp_ge_u32 s26, s22
	s_cselect_b32 s22, s34, s33
	s_abs_i32 s33, s30
	v_cvt_f32_u32_e32 v2, s33
	s_xor_b32 s22, s22, s27
	s_sub_i32 s22, s22, s27
	s_sub_i32 s34, 0, s33
	v_rcp_iflag_f32_e32 v2, v2
	s_mul_i32 s11, s22, s11
	s_sub_i32 s11, s23, s11
	s_lshl_b32 s26, s11, 5
	v_mul_f32_e32 v2, 0x4f7ffffe, v2
	v_cvt_u32_f32_e32 v2, v2
	s_abs_i32 s23, s26
	s_xor_b32 s11, s26, s30
	s_lshl_b32 s22, s22, 6
	v_readfirstlane_b32 s27, v2
	s_mul_i32 s34, s34, s27
	s_mul_hi_u32 s34, s27, s34
	s_add_i32 s27, s27, s34
	s_mul_hi_u32 s27, s23, s27
	s_mul_i32 s34, s27, s33
	s_sub_i32 s23, s23, s34
	s_ashr_i32 s11, s11, 31
	s_add_i32 s34, s27, 1
	s_sub_i32 s35, s23, s33
	s_cmp_ge_u32 s23, s33
	s_cselect_b32 s27, s34, s27
	s_cselect_b32 s23, s35, s23
	s_add_i32 s34, s27, 1
	s_cmp_ge_u32 s23, s33
	s_cselect_b32 s23, s34, s27
	s_xor_b32 s23, s23, s11
	s_sub_i32 s11, s23, s11
	s_mul_i32 s23, s31, s11
	s_mul_i32 s11, s11, s30
	s_sub_i32 s11, s26, s11
	s_add_i32 s11, s23, s11
	s_add_i32 s30, s11, s9
	v_or_b32_e32 v2, s26, v36
	s_ashr_i32 s31, s30, 31
	v_cmp_gt_i32_e32 vcc, s10, v2
	s_lshl_b64 s[10:11], s[30:31], 2
	s_add_u32 s10, s28, s10
	s_addc_u32 s11, s29, s11
	v_or_b32_e32 v47, s22, v1
	v_lshl_add_u64 v[42:43], s[10:11], 0, v[40:41]
	v_mov_b32_e32 v2, 0
	s_and_saveexec_b64 s[10:11], vcc
	s_cbranch_execz .LBB0_20
	v_mad_i64_i32 v[4:5], s[28:29], s8, v47, 0
	v_lshl_add_u64 v[4:5], v[4:5], 2, v[42:43]
	global_load_dwordx4 v[6:9], v[4:5], off nt
.LBB0_20:
	s_or_b64 exec, exec, s[10:11]
	v_mov_b32_e32 v3, 0
	v_mov_b32_e32 v4, 0
	v_mov_b32_e32 v5, 0
	s_and_saveexec_b64 s[10:11], vcc
	s_cbranch_execz .LBB0_22
	v_or_b32_e32 v2, 8, v47
	v_mad_i64_i32 v[2:3], s[28:29], s8, v2, 0
	v_lshl_add_u64 v[2:3], v[2:3], 2, v[42:43]
	global_load_dwordx4 v[2:5], v[2:3], off nt
.LBB0_22:
	s_or_b64 exec, exec, s[10:11]
	v_mov_b32_e32 v10, 0
	v_mov_b32_e32 v14, 0
	v_mov_b32_e32 v15, 0
	v_mov_b32_e32 v16, 0
	v_mov_b32_e32 v17, 0
	s_and_saveexec_b64 s[10:11], vcc
	s_cbranch_execz .LBB0_24
	v_or_b32_e32 v11, 16, v47
	v_mad_i64_i32 v[12:13], s[28:29], s8, v11, 0
	v_lshl_add_u64 v[12:13], v[12:13], 2, v[42:43]
	global_load_dwordx4 v[14:17], v[12:13], off nt
.LBB0_24:
	s_or_b64 exec, exec, s[10:11]
	v_mov_b32_e32 v11, 0
	v_mov_b32_e32 v12, 0
	v_mov_b32_e32 v13, 0
	s_and_saveexec_b64 s[10:11], vcc
	s_cbranch_execz .LBB0_26
	v_or_b32_e32 v10, 24, v47
	v_mad_i64_i32 v[10:11], s[28:29], s8, v10, 0
	v_lshl_add_u64 v[10:11], v[10:11], 2, v[42:43]
	global_load_dwordx4 v[10:13], v[10:11], off nt
.LBB0_26:
	s_or_b64 exec, exec, s[10:11]
	v_mov_b32_e32 v18, 0
	v_mov_b32_e32 v22, 0
	v_mov_b32_e32 v23, 0
	v_mov_b32_e32 v24, 0
	v_mov_b32_e32 v25, 0
	s_and_saveexec_b64 s[10:11], vcc
	s_cbranch_execz .LBB0_28
	v_or_b32_e32 v19, 32, v47
	v_mad_i64_i32 v[20:21], s[28:29], s8, v19, 0
	v_lshl_add_u64 v[20:21], v[20:21], 2, v[42:43]
	global_load_dwordx4 v[22:25], v[20:21], off nt
.LBB0_28:
	s_or_b64 exec, exec, s[10:11]
	v_mov_b32_e32 v19, 0
	v_mov_b32_e32 v20, 0
	v_mov_b32_e32 v21, 0
	s_and_saveexec_b64 s[10:11], vcc
	s_cbranch_execz .LBB0_30
	v_or_b32_e32 v18, 40, v47
	v_mad_i64_i32 v[18:19], s[28:29], s8, v18, 0
	v_lshl_add_u64 v[18:19], v[18:19], 2, v[42:43]
	global_load_dwordx4 v[18:21], v[18:19], off nt
.LBB0_30:
	s_or_b64 exec, exec, s[10:11]
	v_mov_b32_e32 v26, 0
	v_mov_b32_e32 v30, 0
	v_mov_b32_e32 v31, 0
	v_mov_b32_e32 v32, 0
	v_mov_b32_e32 v33, 0
	s_and_saveexec_b64 s[10:11], vcc
	s_cbranch_execz .LBB0_32
	v_or_b32_e32 v27, 48, v47
	v_mad_i64_i32 v[28:29], s[28:29], s8, v27, 0
	v_lshl_add_u64 v[28:29], v[28:29], 2, v[42:43]
	global_load_dwordx4 v[30:33], v[28:29], off nt
.LBB0_32:
	s_or_b64 exec, exec, s[10:11]
	v_mov_b32_e32 v27, 0
	v_mov_b32_e32 v28, 0
	v_mov_b32_e32 v29, 0
	s_and_saveexec_b64 s[10:11], vcc
	s_cbranch_execz .LBB0_9
	v_or_b32_e32 v26, 56, v47
	v_mad_i64_i32 v[26:27], s[8:9], s8, v26, 0
	v_lshl_add_u64 v[26:27], v[26:27], 2, v[42:43]
	global_load_dwordx4 v[26:29], v[26:27], off nt
	s_branch .LBB0_9

; DEV unsigned pk2(float lo, float hi) { f32x2_ v; v.x = lo; v.y = hi; return __builtin_bit_cast(unsigned, __builtin_convertvector(v, bf16x2_)); }
; __global__ void __launch_bounds__(512, 2) fwd_mega(Args args) {
;     ...
;         for (size_t i = gt; i < (size_t)NTOK * DM / 4; i += 4 * GT) {
;             f32x4 v4[4];
; #pragma unroll
;             for (int q = 0; q < 4; ++q) v4[q] = x4[i + q * GT];
; #pragma unroll
;             for (int q = 0; q < 4; ++q) { u32x2 o; o.x = pk2(v4[q].x, v4[q].y); o.y = pk2(v4[q].z, v4[q].w); h2[i + q * GT] = o; } }
.LBB0_36:
	global_load_dwordx4 v[10:13], v[4:5], off nt
	v_lshl_add_u64 v[26:27], v[4:5], 0, s[6:7]
	v_lshl_add_u64 v[28:29], v[4:5], 0, s[16:17]
	v_lshl_add_u64 v[30:31], v[4:5], 0, s[18:19]
	global_load_dwordx4 v[14:17], v[26:27], off nt
	global_load_dwordx4 v[18:21], v[28:29], off nt
	global_load_dwordx4 v[22:25], v[30:31], off nt
	v_lshl_add_u64 v[8:9], v[8:9], 0, s[40:41]
	v_cmp_lt_u64_e32 vcc, s[24:25], v[8:9]
	v_lshl_add_u64 v[26:27], v[6:7], 0, s[8:9]
	v_lshl_add_u64 v[28:29], v[6:7], 0, s[6:7]
	v_lshl_add_u64 v[30:31], v[6:7], 0, s[20:21]
	v_lshl_add_u64 v[4:5], v[4:5], 0, s[10:11]
	s_or_b64 s[22:23], vcc, s[22:23]
	s_waitcnt vmcnt(3)
	v_cvt_pk_bf16_f32 v10, v10, v11
	v_cvt_pk_bf16_f32 v11, v12, v13
	global_store_dwordx2 v[6:7], v[10:11], off
	s_waitcnt vmcnt(3)
	v_cvt_pk_bf16_f32 v10, v14, v15
	v_cvt_pk_bf16_f32 v11, v16, v17
	v_lshl_add_u64 v[6:7], v[6:7], 0, s[16:17]
	s_waitcnt vmcnt(2)
	v_cvt_pk_bf16_f32 v12, v18, v19
	v_cvt_pk_bf16_f32 v13, v20, v21
	s_waitcnt vmcnt(1)
	v_cvt_pk_bf16_f32 v14, v22, v23
	v_cvt_pk_bf16_f32 v15, v24, v25
	global_store_dwordx2 v[26:27], v[10:11], off
	global_store_dwordx2 v[28:29], v[12:13], off
	global_store_dwordx2 v[30:31], v[14:15], off
	s_andn2_b64 exec, exec, s[22:23]
	s_cbranch_execnz .LBB0_36
